# MLA loop: P.V MFMAs issued k-step-major so the P fragment operand repeats for four consecutive MFMAs (fewer operand toggles), same per-accumulator order
# baseline (speedup 1.0000x reference)
.Lmla_loop:
	ds_read_b128 v[214:217], v166 offset:32768
	ds_read_b128 v[218:221], v166 offset:40960
	ds_read_b128 v[222:225], v167 offset:32768
	ds_read_b128 v[226:229], v167 offset:40960
	ds_read_b128 v[230:233], v168 offset:32768
	ds_read_b128 v[234:237], v168 offset:40960
	v_lshl_add_u32 v183, s52, 14, v161
	s_mov_b32 m0, s45
	s_lshl_b32 s8, s49, 14
	global_load_lds_dwordx4 v178, s[98:99]
	v_exp_f32_e32 v144, v144
	v_add_f32_e32 v243, v128, v129
	v_add_f32_e32 v244, v130, v131
	v_exp_f32_e32 v145, v145
	s_waitcnt lgkmcnt(4)
	v_mfma_f32_32x32x16_bf16 v[64:79], v[214:217], v[124:127], v[198:213]
	s_mov_b32 m0, s77
	s_add_i32 s12, s8, s44
	global_load_lds_dwordx4 v179, s[98:99]
	v_cvt_pk_bf16_f32 v128, v128, v129
	v_add_f32_e32 v243, v132, v243
	v_exp_f32_e32 v146, v146
	v_mfma_f32_32x32x16_bf16 v[80:95], v[218:221], v[124:127], v[198:213]
	ds_read_b128 v[214:217], v169 offset:32768
	ds_read_b128 v[218:221], v169 offset:40960
	v_cvt_pk_bf16_f32 v129, v130, v131
	v_add_f32_e32 v244, v133, v244
	v_exp_f32_e32 v147, v147
	s_waitcnt lgkmcnt(4)
	v_mfma_f32_32x32x16_bf16 v[64:79], v[222:225], v[120:123], v[64:79]
	s_mov_b32 m0, s12
	s_add_i32 s12, s8, s47
	global_load_lds_dwordx4 v180, s[98:99]
	v_add_f32_e32 v243, v134, v243
	v_cvt_pk_bf16_f32 v130, v132, v133
	v_exp_f32_e32 v148, v148
	v_mfma_f32_32x32x16_bf16 v[80:95], v[226:229], v[120:123], v[80:95]
	ds_read_b128 v[222:225], v170 offset:32768
	ds_read_b128 v[226:229], v170 offset:40960
	v_add_f32_e32 v244, v135, v244
	v_exp_f32_e32 v149, v149
	v_add_f32_e32 v243, v136, v243
	s_waitcnt lgkmcnt(4)
	v_mfma_f32_32x32x16_bf16 v[64:79], v[230:233], v[116:119], v[64:79]
	s_mov_b32 m0, s12
	s_nop 0
	global_load_lds_dwordx4 v181, s[98:99]
	v_cvt_pk_bf16_f32 v131, v134, v135
	v_exp_f32_e32 v150, v150
	v_add_f32_e32 v244, v137, v244
	v_mfma_f32_32x32x16_bf16 v[80:95], v[234:237], v[116:119], v[80:95]
	ds_read_b128 v[230:233], v171 offset:32768
	ds_read_b128 v[234:237], v171 offset:40960
	v_exp_f32_e32 v151, v151
	v_add_f32_e32 v243, v138, v243
	v_permlane32_swap_b32_e32 v128, v130
	s_waitcnt lgkmcnt(4)
	v_mfma_f32_32x32x16_bf16 v[64:79], v[214:217], v[112:115], v[64:79]
	s_mov_b32 m0, s9
	s_nop 0
	global_load_lds_dwordx4 v182, s[100:101]
	s_add_u32 s98, s98, 0x40000
	s_addc_u32 s99, s99, 0
	s_add_u32 s100, s100, 0x2000
	s_addc_u32 s101, s101, 0
	v_cvt_pk_bf16_f32 v132, v136, v137
	v_exp_f32_e32 v152, v152
	v_add_f32_e32 v244, v139, v244
	v_mfma_f32_32x32x16_bf16 v[80:95], v[218:221], v[112:115], v[80:95]
	ds_read_b128 v[214:217], v172 offset:32768
	ds_read_b128 v[218:221], v172 offset:40960
	v_exp_f32_e32 v153, v153
	v_add_f32_e32 v243, v140, v243
	v_permlane32_swap_b32_e32 v129, v131
	s_waitcnt lgkmcnt(4)
	v_mfma_f32_32x32x16_bf16 v[64:79], v[222:225], v[108:111], v[64:79]
	v_cvt_pk_bf16_f32 v133, v138, v139
	v_add_f32_e32 v244, v141, v244
	v_exp_f32_e32 v154, v154
	v_mfma_f32_32x32x16_bf16 v[80:95], v[226:229], v[108:111], v[80:95]
	ds_read_b128 v[222:225], v173 offset:32768
	ds_read_b128 v[226:229], v173 offset:40960
	v_add_f32_e32 v243, v142, v243
	v_exp_f32_e32 v155, v155
	v_cvt_pk_bf16_f32 v134, v140, v141
	s_waitcnt lgkmcnt(4)
	v_mfma_f32_32x32x16_bf16 v[64:79], v[230:233], v[104:107], v[64:79]
	v_add_f32_e32 v244, v143, v244
	v_exp_f32_e32 v156, v156
	v_add_f32_e32 v243, v144, v243
	v_mfma_f32_32x32x16_bf16 v[80:95], v[234:237], v[104:107], v[80:95]
	ds_read_b128 v[230:233], v174 offset:8192
	ds_read_b128 v[234:237], v174 offset:12288
	v_cvt_pk_bf16_f32 v135, v142, v143
	v_exp_f32_e32 v157, v157
	v_add_f32_e32 v244, v145, v244
	s_waitcnt lgkmcnt(4)
	v_mfma_f32_32x32x16_bf16 v[64:79], v[214:217], v[100:103], v[64:79]
	v_exp_f32_e32 v158, v158
	v_add_f32_e32 v243, v146, v243
	v_permlane32_swap_b32_e32 v132, v134
	v_mfma_f32_32x32x16_bf16 v[80:95], v[218:221], v[100:103], v[80:95]
	ds_read_b128 v[214:217], v175 offset:8192
	ds_read_b128 v[218:221], v175 offset:12288
	v_cvt_pk_bf16_f32 v144, v144, v145
	v_exp_f32_e32 v159, v159
	v_add_f32_e32 v244, v147, v244
	s_waitcnt lgkmcnt(4)
	v_mfma_f32_32x32x16_bf16 v[64:79], v[222:225], v[96:99], v[64:79]
	v_add_f32_e32 v243, v148, v243
	v_permlane32_swap_b32_e32 v133, v135
	v_cvt_pk_bf16_f32 v145, v146, v147
	v_add_f32_e32 v244, v149, v244
	v_mfma_f32_32x32x16_bf16 v[80:95], v[226:229], v[96:99], v[80:95]
	ds_read_b128 v[222:225], v176 offset:8192
	ds_read_b128 v[226:229], v176 offset:12288
	v_add_f32_e32 v243, v150, v243
	v_cvt_pk_bf16_f32 v146, v148, v149
	v_add_f32_e32 v244, v151, v244
	v_add_f32_e32 v243, v152, v243
	s_waitcnt lgkmcnt(4)
	v_mfma_f32_32x32x16_bf16 v[64:79], v[230:233], v[246:249], v[64:79]
	v_cvt_pk_bf16_f32 v147, v150, v151
	v_add_f32_e32 v244, v153, v244
	v_add_f32_e32 v243, v154, v243
	v_permlane32_swap_b32_e32 v144, v146
	v_mfma_f32_32x32x16_bf16 v[80:95], v[234:237], v[246:249], v[80:95]
	ds_read_b128 v[230:233], v177 offset:8192
	ds_read_b128 v[234:237], v177 offset:12288
	v_cvt_pk_bf16_f32 v148, v152, v153
	v_add_f32_e32 v244, v155, v244
	v_add_f32_e32 v243, v156, v243
	v_permlane32_swap_b32_e32 v145, v147
	s_waitcnt lgkmcnt(4)
	v_mfma_f32_32x32x16_bf16 v[64:79], v[214:217], v[250:253], v[64:79]
	v_cvt_pk_bf16_f32 v149, v154, v155
	v_add_f32_e32 v244, v157, v244
	v_add_f32_e32 v243, v158, v243
	v_cvt_pk_bf16_f32 v150, v156, v157
	v_mfma_f32_32x32x16_bf16 v[80:95], v[218:221], v[250:253], v[80:95]
	ds_read_b64_tr_b16 v[214:215], v183
	ds_read_b64_tr_b16 v[216:217], v183 offset:2048
	ds_read_b64_tr_b16 v[218:219], v183 offset:512
	ds_read_b64_tr_b16 v[220:221], v183 offset:2560
	v_add_f32_e32 v244, v159, v244
	v_cvt_pk_bf16_f32 v151, v158, v159
	v_permlane32_swap_b32_e32 v148, v150
	v_add_f32_e32 v243, v243, v244
	s_waitcnt lgkmcnt(6)
	v_mfma_f32_32x32x16_bf16 v[64:79], v[222:225], v[186:189], v[64:79]
	v_permlane32_swap_b32_e32 v149, v151
	v_mov_b32_e32 v244, v243
	v_mfma_f32_32x32x16_bf16 v[80:95], v[226:229], v[186:189], v[80:95]
	ds_read_b64_tr_b16 v[222:223], v183 offset:1024
	ds_read_b64_tr_b16 v[224:225], v183 offset:3072
	ds_read_b64_tr_b16 v[226:227], v183 offset:1536
	ds_read_b64_tr_b16 v[228:229], v183 offset:3584
	v_permlane32_swap_b32_e32 v243, v244
	v_add_f32_e32 v243, v243, v244
	v_fma_f32 v163, v163, v242, v243
	s_waitcnt lgkmcnt(8)
	v_mfma_f32_32x32x16_bf16 v[64:79], v[230:233], v[238:241], v[64:79]
	v_mfma_f32_32x32x16_bf16 v[80:95], v[234:237], v[238:241], v[80:95]
	s_waitcnt lgkmcnt(6)
	v_mfma_f32_32x32x16_bf16 v[0:15], v[128:131], v[214:217], v[0:15]
	ds_read_b64_tr_b16 v[136:137], v183 offset:4096
	ds_read_b64_tr_b16 v[138:139], v183 offset:6144
	s_waitcnt lgkmcnt(6)
	v_mfma_f32_32x32x16_bf16 v[48:63], v[128:131], v[218:221], v[48:63]
	ds_read_b64_tr_b16 v[140:141], v183 offset:4608
	ds_read_b64_tr_b16 v[142:143], v183 offset:6656
	s_waitcnt lgkmcnt(6)
	v_mfma_f32_32x32x16_bf16 v[32:47], v[128:131], v[222:225], v[32:47]
	ds_read_b64_tr_b16 v[152:153], v183 offset:5120
	ds_read_b64_tr_b16 v[154:155], v183 offset:7168
	v_max3_f32 v196, v64, v65, v66
	v_max3_f32 v197, v80, v81, v82
	v_max3_f32 v196, v196, v67, v68
	v_max3_f32 v197, v197, v83, v84
	v_max3_f32 v196, v196, v69, v70
	v_max3_f32 v197, v197, v85, v86
	s_waitcnt lgkmcnt(6)
	v_mfma_f32_32x32x16_bf16 v[16:31], v[128:131], v[226:229], v[16:31]
	ds_read_b64_tr_b16 v[156:157], v183 offset:5632
	ds_read_b64_tr_b16 v[158:159], v183 offset:7680
	v_max3_f32 v196, v196, v71, v72
	v_max3_f32 v197, v197, v87, v88
	v_max3_f32 v196, v196, v73, v74
	v_max3_f32 v197, v197, v89, v90
	v_max3_f32 v196, v196, v75, v76
	v_max3_f32 v197, v197, v91, v92
	s_waitcnt lgkmcnt(6)
	v_mfma_f32_32x32x16_bf16 v[0:15], v[132:135], v[136:139], v[0:15]
	ds_read_b64_tr_b16 v[214:215], v183 offset:8192
	ds_read_b64_tr_b16 v[216:217], v183 offset:10240
	v_max3_f32 v196, v196, v77, v78
	v_max3_f32 v197, v197, v93, v94
	v_max_f32_e32 v196, v196, v79
	v_max_f32_e32 v197, v197, v95
	v_max_f32_e32 v196, v196, v197
	v_mov_b32_e32 v197, v196
	s_waitcnt lgkmcnt(6)
	v_mfma_f32_32x32x16_bf16 v[48:63], v[132:135], v[140:143], v[48:63]
	ds_read_b64_tr_b16 v[218:219], v183 offset:8704
	ds_read_b64_tr_b16 v[220:221], v183 offset:10752
	v_permlane32_swap_b32_e32 v196, v197
	v_max_f32_e32 v196, v196, v197
	v_cmp_ge_f32_e32 vcc, s97, v196
	s_cmp_eq_u64 vcc, exec
	s_cselect_b64 s[42:43], -1, 0
	v_mov_b32_e32 v193, 1.0
	s_mov_b64 s[12:13], 0
	s_cmp_lg_u64 s[42:43], 0
	s_cbranch_scc1 .Lmla_ok_A
	v_max_f32_e32 v197, 0, v196
	v_exp_f32_e64 v193, -v197
	v_sub_f32_e32 v64, v64, v197
	v_sub_f32_e32 v65, v65, v197
	v_sub_f32_e32 v66, v66, v197
	v_sub_f32_e32 v67, v67, v197
	v_sub_f32_e32 v68, v68, v197
	v_sub_f32_e32 v69, v69, v197
	v_sub_f32_e32 v70, v70, v197
	v_sub_f32_e32 v71, v71, v197
	v_sub_f32_e32 v72, v72, v197
	v_sub_f32_e32 v73, v73, v197
	v_sub_f32_e32 v74, v74, v197
	v_sub_f32_e32 v75, v75, v197
	v_sub_f32_e32 v76, v76, v197
	v_sub_f32_e32 v77, v77, v197
	v_sub_f32_e32 v78, v78, v197
	v_sub_f32_e32 v79, v79, v197
	v_sub_f32_e32 v80, v80, v197
	v_sub_f32_e32 v81, v81, v197
	v_sub_f32_e32 v82, v82, v197
	v_sub_f32_e32 v83, v83, v197
	v_sub_f32_e32 v84, v84, v197
	v_sub_f32_e32 v85, v85, v197
	v_sub_f32_e32 v86, v86, v197
	v_sub_f32_e32 v87, v87, v197
	v_sub_f32_e32 v88, v88, v197
	v_sub_f32_e32 v89, v89, v197
	v_sub_f32_e32 v90, v90, v197
	v_sub_f32_e32 v91, v91, v197
	v_sub_f32_e32 v92, v92, v197
	v_sub_f32_e32 v93, v93, v197
	v_sub_f32_e32 v94, v94, v197
	v_sub_f32_e32 v95, v95, v197
	v_sub_f32_e32 v198, v198, v197
	v_sub_f32_e32 v199, v199, v197
	v_sub_f32_e32 v200, v200, v197
	v_sub_f32_e32 v201, v201, v197
	v_sub_f32_e32 v202, v202, v197
	v_sub_f32_e32 v203, v203, v197
	v_sub_f32_e32 v204, v204, v197
	v_sub_f32_e32 v205, v205, v197
	v_sub_f32_e32 v206, v206, v197
	v_sub_f32_e32 v207, v207, v197
	v_sub_f32_e32 v208, v208, v197
	v_sub_f32_e32 v209, v209, v197
	v_sub_f32_e32 v210, v210, v197
	v_sub_f32_e32 v211, v211, v197
	v_sub_f32_e32 v212, v212, v197
	v_sub_f32_e32 v213, v213, v197
	v_cmp_gt_f32_e64 s[12:13], 1.0, v193
.Lmla_ok_A:
	s_waitcnt lgkmcnt(6)
	v_mfma_f32_32x32x16_bf16 v[32:47], v[132:135], v[152:155], v[32:47]
	ds_read_b64_tr_b16 v[222:223], v183 offset:9216
	ds_read_b64_tr_b16 v[224:225], v183 offset:11264
	v_exp_f32_e32 v64, v64
	v_exp_f32_e32 v65, v65
	v_exp_f32_e32 v66, v66
	s_waitcnt lgkmcnt(6)
	v_mfma_f32_32x32x16_bf16 v[16:31], v[132:135], v[156:159], v[16:31]
	ds_read_b64_tr_b16 v[226:227], v183 offset:9728
	ds_read_b64_tr_b16 v[228:229], v183 offset:11776
	v_exp_f32_e32 v67, v67
	v_exp_f32_e32 v68, v68
	v_exp_f32_e32 v69, v69
	s_waitcnt lgkmcnt(6)
	v_mfma_f32_32x32x16_bf16 v[0:15], v[144:147], v[214:217], v[0:15]
	ds_read_b64_tr_b16 v[136:137], v183 offset:12288
	ds_read_b64_tr_b16 v[138:139], v183 offset:14336
	v_exp_f32_e32 v70, v70
	v_exp_f32_e32 v71, v71
	v_exp_f32_e32 v72, v72
	s_waitcnt lgkmcnt(6)
	v_mfma_f32_32x32x16_bf16 v[48:63], v[144:147], v[218:221], v[48:63]
	ds_read_b64_tr_b16 v[140:141], v183 offset:12800
	ds_read_b64_tr_b16 v[142:143], v183 offset:14848
	v_exp_f32_e32 v73, v73
	v_exp_f32_e32 v74, v74
	v_exp_f32_e32 v75, v75
	s_waitcnt lgkmcnt(6)
	v_mfma_f32_32x32x16_bf16 v[32:47], v[144:147], v[222:225], v[32:47]
	ds_read_b64_tr_b16 v[152:153], v183 offset:13312
	ds_read_b64_tr_b16 v[154:155], v183 offset:15360
	v_exp_f32_e32 v76, v76
	v_exp_f32_e32 v77, v77
	v_exp_f32_e32 v78, v78
	s_waitcnt lgkmcnt(6)
	v_mfma_f32_32x32x16_bf16 v[16:31], v[144:147], v[226:229], v[16:31]
	ds_read_b64_tr_b16 v[156:157], v183 offset:13824
	ds_read_b64_tr_b16 v[158:159], v183 offset:15872
	v_exp_f32_e32 v79, v79
	s_waitcnt lgkmcnt(6)
	v_mfma_f32_32x32x16_bf16 v[0:15], v[148:151], v[136:139], v[0:15]
	s_waitcnt lgkmcnt(4)
	v_mfma_f32_32x32x16_bf16 v[48:63], v[148:151], v[140:143], v[48:63]
	s_waitcnt lgkmcnt(2)
	v_mfma_f32_32x32x16_bf16 v[32:47], v[148:151], v[152:155], v[32:47]
	s_waitcnt lgkmcnt(0)
	v_mfma_f32_32x32x16_bf16 v[16:31], v[148:151], v[156:159], v[16:31]
	s_cmp_lg_u64 s[12:13], 0
	s_cbranch_scc0 .Lmla_nors_A
	s_and_saveexec_b64 s[20:21], s[40:41]
	ds_write_b32 v162, v193 offset:128
	s_or_b64 exec, exec, s[20:21]
	s_waitcnt lgkmcnt(0)
	v_add_u32_e32 v245, s37, v184
	ds_read_b128 v[214:217], v245 offset:128
	ds_read_b128 v[218:221], v245 offset:160
	ds_read_b128 v[222:225], v245 offset:192
	ds_read_b128 v[226:229], v245 offset:224
	s_waitcnt lgkmcnt(0)
	v_pk_mul_f32 v[0:1], v[0:1], v[214:215]
	v_pk_mul_f32 v[2:3], v[2:3], v[216:217]
	v_pk_mul_f32 v[4:5], v[4:5], v[218:219]
	v_pk_mul_f32 v[6:7], v[6:7], v[220:221]
	v_pk_mul_f32 v[8:9], v[8:9], v[222:223]
	v_pk_mul_f32 v[10:11], v[10:11], v[224:225]
	v_pk_mul_f32 v[12:13], v[12:13], v[226:227]
	v_pk_mul_f32 v[14:15], v[14:15], v[228:229]
	v_pk_mul_f32 v[48:49], v[48:49], v[214:215]
	v_pk_mul_f32 v[50:51], v[50:51], v[216:217]
	v_pk_mul_f32 v[52:53], v[52:53], v[218:219]
	v_pk_mul_f32 v[54:55], v[54:55], v[220:221]
	v_pk_mul_f32 v[56:57], v[56:57], v[222:223]
	v_pk_mul_f32 v[58:59], v[58:59], v[224:225]
	v_pk_mul_f32 v[60:61], v[60:61], v[226:227]
	v_pk_mul_f32 v[62:63], v[62:63], v[228:229]
	v_pk_mul_f32 v[32:33], v[32:33], v[214:215]
	v_pk_mul_f32 v[34:35], v[34:35], v[216:217]
	v_pk_mul_f32 v[36:37], v[36:37], v[218:219]
	v_pk_mul_f32 v[38:39], v[38:39], v[220:221]
	v_pk_mul_f32 v[40:41], v[40:41], v[222:223]
	v_pk_mul_f32 v[42:43], v[42:43], v[224:225]
	v_pk_mul_f32 v[44:45], v[44:45], v[226:227]
	v_pk_mul_f32 v[46:47], v[46:47], v[228:229]
	v_pk_mul_f32 v[16:17], v[16:17], v[214:215]
	v_pk_mul_f32 v[18:19], v[18:19], v[216:217]
	v_pk_mul_f32 v[20:21], v[20:21], v[218:219]
	v_pk_mul_f32 v[22:23], v[22:23], v[220:221]
	v_pk_mul_f32 v[24:25], v[24:25], v[222:223]
	v_pk_mul_f32 v[26:27], v[26:27], v[224:225]
	v_pk_mul_f32 v[28:29], v[28:29], v[226:227]
	v_pk_mul_f32 v[30:31], v[30:31], v[228:229]
.Lmla_nors_A:
	s_add_i32 s8, s52, 1
	s_cmp_lg_u32 s52, 2
	s_cselect_b32 s14, s8, 0
	s_add_i32 s8, s49, 1
	s_cmp_lg_u32 s49, 2
	s_cselect_b32 s15, s8, 0
	s_waitcnt vmcnt(0) lgkmcnt(0)
	s_barrier
	ds_read_b128 v[214:217], v166 offset:16384
	ds_read_b128 v[218:221], v166 offset:24576
	ds_read_b128 v[222:225], v167 offset:16384
	ds_read_b128 v[226:229], v167 offset:24576
	ds_read_b128 v[230:233], v168 offset:16384
	ds_read_b128 v[234:237], v168 offset:24576
	v_lshl_add_u32 v183, s14, 14, v161
	s_mov_b32 m0, s93
	s_lshl_b32 s8, s15, 14
	global_load_lds_dwordx4 v178, s[98:99]
	v_exp_f32_e32 v80, v80
	v_add_f32_e32 v243, v64, v65
	v_add_f32_e32 v244, v66, v67
	v_exp_f32_e32 v81, v81
	s_waitcnt lgkmcnt(4)
	v_mfma_f32_32x32x16_bf16 v[128:143], v[214:217], v[124:127], v[198:213]
	s_mov_b32 m0, s50
	s_add_i32 s12, s8, s44
	global_load_lds_dwordx4 v179, s[98:99]
	v_cvt_pk_bf16_f32 v64, v64, v65
	v_add_f32_e32 v243, v68, v243
	v_exp_f32_e32 v82, v82
	v_mfma_f32_32x32x16_bf16 v[144:159], v[218:221], v[124:127], v[198:213]
	ds_read_b128 v[214:217], v169 offset:16384
	ds_read_b128 v[218:221], v169 offset:24576
	v_cvt_pk_bf16_f32 v65, v66, v67
	v_add_f32_e32 v244, v69, v244
	v_exp_f32_e32 v83, v83
	s_waitcnt lgkmcnt(4)
	v_mfma_f32_32x32x16_bf16 v[128:143], v[222:225], v[120:123], v[128:143]
	s_mov_b32 m0, s12
	s_add_i32 s12, s8, s47
	global_load_lds_dwordx4 v180, s[98:99]
	v_add_f32_e32 v243, v70, v243
	v_cvt_pk_bf16_f32 v66, v68, v69
	v_exp_f32_e32 v84, v84
	v_mfma_f32_32x32x16_bf16 v[144:159], v[226:229], v[120:123], v[144:159]
	ds_read_b128 v[222:225], v170 offset:16384
	ds_read_b128 v[226:229], v170 offset:24576
	v_add_f32_e32 v244, v71, v244
	v_exp_f32_e32 v85, v85
	v_add_f32_e32 v243, v72, v243
	s_waitcnt lgkmcnt(4)
	v_mfma_f32_32x32x16_bf16 v[128:143], v[230:233], v[116:119], v[128:143]
	s_mov_b32 m0, s12
	s_nop 0
	global_load_lds_dwordx4 v181, s[98:99]
	v_cvt_pk_bf16_f32 v67, v70, v71
	v_exp_f32_e32 v86, v86
	v_add_f32_e32 v244, v73, v244
	v_mfma_f32_32x32x16_bf16 v[144:159], v[234:237], v[116:119], v[144:159]
	ds_read_b128 v[230:233], v171 offset:16384
	ds_read_b128 v[234:237], v171 offset:24576
	v_exp_f32_e32 v87, v87
	v_add_f32_e32 v243, v74, v243
	v_permlane32_swap_b32_e32 v64, v66
	s_waitcnt lgkmcnt(4)
	v_mfma_f32_32x32x16_bf16 v[128:143], v[214:217], v[112:115], v[128:143]
	s_mov_b32 m0, s51
	s_nop 0
	global_load_lds_dwordx4 v182, s[100:101]
	s_add_u32 s98, s98, 0x40000
	s_addc_u32 s99, s99, 0
	s_add_u32 s100, s100, 0x2000
	s_addc_u32 s101, s101, 0
	v_cvt_pk_bf16_f32 v68, v72, v73
	v_exp_f32_e32 v88, v88
	v_add_f32_e32 v244, v75, v244
	v_mfma_f32_32x32x16_bf16 v[144:159], v[218:221], v[112:115], v[144:159]
	ds_read_b128 v[214:217], v172 offset:16384
	ds_read_b128 v[218:221], v172 offset:24576
	v_exp_f32_e32 v89, v89
	v_add_f32_e32 v243, v76, v243
	v_permlane32_swap_b32_e32 v65, v67
	s_waitcnt lgkmcnt(4)
	v_mfma_f32_32x32x16_bf16 v[128:143], v[222:225], v[108:111], v[128:143]
	v_cvt_pk_bf16_f32 v69, v74, v75
	v_add_f32_e32 v244, v77, v244
	v_exp_f32_e32 v90, v90
	v_mfma_f32_32x32x16_bf16 v[144:159], v[226:229], v[108:111], v[144:159]
	ds_read_b128 v[222:225], v173 offset:16384
	ds_read_b128 v[226:229], v173 offset:24576
	v_add_f32_e32 v243, v78, v243
	v_exp_f32_e32 v91, v91
	v_cvt_pk_bf16_f32 v70, v76, v77
	s_waitcnt lgkmcnt(4)
	v_mfma_f32_32x32x16_bf16 v[128:143], v[230:233], v[104:107], v[128:143]
	v_add_f32_e32 v244, v79, v244
	v_exp_f32_e32 v92, v92
	v_add_f32_e32 v243, v80, v243
	v_mfma_f32_32x32x16_bf16 v[144:159], v[234:237], v[104:107], v[144:159]
	ds_read_b128 v[230:233], v174
	ds_read_b128 v[234:237], v174 offset:4096
	v_cvt_pk_bf16_f32 v71, v78, v79
	v_exp_f32_e32 v93, v93
	v_add_f32_e32 v244, v81, v244
	s_waitcnt lgkmcnt(4)
	v_mfma_f32_32x32x16_bf16 v[128:143], v[214:217], v[100:103], v[128:143]
	v_exp_f32_e32 v94, v94
	v_add_f32_e32 v243, v82, v243
	v_permlane32_swap_b32_e32 v68, v70
	v_mfma_f32_32x32x16_bf16 v[144:159], v[218:221], v[100:103], v[144:159]
	ds_read_b128 v[214:217], v175
	ds_read_b128 v[218:221], v175 offset:4096
	v_cvt_pk_bf16_f32 v80, v80, v81
	v_exp_f32_e32 v95, v95
	v_add_f32_e32 v244, v83, v244
	s_waitcnt lgkmcnt(4)
	v_mfma_f32_32x32x16_bf16 v[128:143], v[222:225], v[96:99], v[128:143]
	v_add_f32_e32 v243, v84, v243
	v_permlane32_swap_b32_e32 v69, v71
	v_cvt_pk_bf16_f32 v81, v82, v83
	v_add_f32_e32 v244, v85, v244
	v_mfma_f32_32x32x16_bf16 v[144:159], v[226:229], v[96:99], v[144:159]
	ds_read_b128 v[222:225], v176
	ds_read_b128 v[226:229], v176 offset:4096
	v_add_f32_e32 v243, v86, v243
	v_cvt_pk_bf16_f32 v82, v84, v85
	v_add_f32_e32 v244, v87, v244
	v_add_f32_e32 v243, v88, v243
	s_waitcnt lgkmcnt(4)
	v_mfma_f32_32x32x16_bf16 v[128:143], v[230:233], v[246:249], v[128:143]
	v_cvt_pk_bf16_f32 v83, v86, v87
	v_add_f32_e32 v244, v89, v244
	v_add_f32_e32 v243, v90, v243
	v_permlane32_swap_b32_e32 v80, v82
	v_mfma_f32_32x32x16_bf16 v[144:159], v[234:237], v[246:249], v[144:159]
	ds_read_b128 v[230:233], v177
	ds_read_b128 v[234:237], v177 offset:4096
	v_cvt_pk_bf16_f32 v84, v88, v89
	v_add_f32_e32 v244, v91, v244
	v_add_f32_e32 v243, v92, v243
	v_permlane32_swap_b32_e32 v81, v83
	s_waitcnt lgkmcnt(4)
	v_mfma_f32_32x32x16_bf16 v[128:143], v[214:217], v[250:253], v[128:143]
	v_cvt_pk_bf16_f32 v85, v90, v91
	v_add_f32_e32 v244, v93, v244
	v_add_f32_e32 v243, v94, v243
	v_cvt_pk_bf16_f32 v86, v92, v93
	v_mfma_f32_32x32x16_bf16 v[144:159], v[218:221], v[250:253], v[144:159]
	ds_read_b64_tr_b16 v[214:215], v183
	ds_read_b64_tr_b16 v[216:217], v183 offset:2048
	ds_read_b64_tr_b16 v[218:219], v183 offset:512
	ds_read_b64_tr_b16 v[220:221], v183 offset:2560
	v_add_f32_e32 v244, v95, v244
	v_cvt_pk_bf16_f32 v87, v94, v95
	v_permlane32_swap_b32_e32 v84, v86
	v_add_f32_e32 v243, v243, v244
	s_waitcnt lgkmcnt(6)
	v_mfma_f32_32x32x16_bf16 v[128:143], v[222:225], v[186:189], v[128:143]
	v_permlane32_swap_b32_e32 v85, v87
	v_mov_b32_e32 v244, v243
	v_mfma_f32_32x32x16_bf16 v[144:159], v[226:229], v[186:189], v[144:159]
	ds_read_b64_tr_b16 v[222:223], v183 offset:1024
	ds_read_b64_tr_b16 v[224:225], v183 offset:3072
	ds_read_b64_tr_b16 v[226:227], v183 offset:1536
	ds_read_b64_tr_b16 v[228:229], v183 offset:3584
	v_permlane32_swap_b32_e32 v243, v244
	v_add_f32_e32 v243, v243, v244
	v_fma_f32 v163, v163, v193, v243
	s_waitcnt lgkmcnt(8)
	v_mfma_f32_32x32x16_bf16 v[128:143], v[230:233], v[238:241], v[128:143]
	v_mfma_f32_32x32x16_bf16 v[144:159], v[234:237], v[238:241], v[144:159]
	s_waitcnt lgkmcnt(6)
	v_mfma_f32_32x32x16_bf16 v[0:15], v[64:67], v[214:217], v[0:15]
	ds_read_b64_tr_b16 v[72:73], v183 offset:4096
	ds_read_b64_tr_b16 v[74:75], v183 offset:6144
	s_waitcnt lgkmcnt(6)
	v_mfma_f32_32x32x16_bf16 v[48:63], v[64:67], v[218:221], v[48:63]
	ds_read_b64_tr_b16 v[76:77], v183 offset:4608
	ds_read_b64_tr_b16 v[78:79], v183 offset:6656
	s_waitcnt lgkmcnt(6)
	v_mfma_f32_32x32x16_bf16 v[32:47], v[64:67], v[222:225], v[32:47]
	ds_read_b64_tr_b16 v[88:89], v183 offset:5120
	ds_read_b64_tr_b16 v[90:91], v183 offset:7168
	v_max3_f32 v196, v128, v129, v130
	v_max3_f32 v197, v144, v145, v146
	v_max3_f32 v196, v196, v131, v132
	v_max3_f32 v197, v197, v147, v148
	v_max3_f32 v196, v196, v133, v134
	v_max3_f32 v197, v197, v149, v150
	s_waitcnt lgkmcnt(6)
	v_mfma_f32_32x32x16_bf16 v[16:31], v[64:67], v[226:229], v[16:31]
	ds_read_b64_tr_b16 v[92:93], v183 offset:5632
	ds_read_b64_tr_b16 v[94:95], v183 offset:7680
	v_max3_f32 v196, v196, v135, v136
	v_max3_f32 v197, v197, v151, v152
	v_max3_f32 v196, v196, v137, v138
	v_max3_f32 v197, v197, v153, v154
	v_max3_f32 v196, v196, v139, v140
	v_max3_f32 v197, v197, v155, v156
	s_waitcnt lgkmcnt(6)
	v_mfma_f32_32x32x16_bf16 v[0:15], v[68:71], v[72:75], v[0:15]
	ds_read_b64_tr_b16 v[214:215], v183 offset:8192
	ds_read_b64_tr_b16 v[216:217], v183 offset:10240
	v_max3_f32 v196, v196, v141, v142
	v_max3_f32 v197, v197, v157, v158
	v_max_f32_e32 v196, v196, v143
	v_max_f32_e32 v197, v197, v159
	v_max_f32_e32 v196, v196, v197
	v_mov_b32_e32 v197, v196
	s_waitcnt lgkmcnt(6)
	v_mfma_f32_32x32x16_bf16 v[48:63], v[68:71], v[76:79], v[48:63]
	ds_read_b64_tr_b16 v[218:219], v183 offset:8704
	ds_read_b64_tr_b16 v[220:221], v183 offset:10752
	v_permlane32_swap_b32_e32 v196, v197
	v_max_f32_e32 v196, v196, v197
	v_cmp_ge_f32_e32 vcc, s97, v196
	s_cmp_eq_u64 vcc, exec
	s_cselect_b64 s[42:43], -1, 0
	v_mov_b32_e32 v242, 1.0
	s_mov_b64 s[12:13], 0
	s_cmp_lg_u64 s[42:43], 0
	s_cbranch_scc1 .Lmla_ok_B
	v_max_f32_e32 v197, 0, v196
	v_exp_f32_e64 v242, -v197
	v_sub_f32_e32 v128, v128, v197
	v_sub_f32_e32 v129, v129, v197
	v_sub_f32_e32 v130, v130, v197
	v_sub_f32_e32 v131, v131, v197
	v_sub_f32_e32 v132, v132, v197
	v_sub_f32_e32 v133, v133, v197
	v_sub_f32_e32 v134, v134, v197
	v_sub_f32_e32 v135, v135, v197
	v_sub_f32_e32 v136, v136, v197
	v_sub_f32_e32 v137, v137, v197
	v_sub_f32_e32 v138, v138, v197
	v_sub_f32_e32 v139, v139, v197
	v_sub_f32_e32 v140, v140, v197
	v_sub_f32_e32 v141, v141, v197
	v_sub_f32_e32 v142, v142, v197
	v_sub_f32_e32 v143, v143, v197
	v_sub_f32_e32 v144, v144, v197
	v_sub_f32_e32 v145, v145, v197
	v_sub_f32_e32 v146, v146, v197
	v_sub_f32_e32 v147, v147, v197
	v_sub_f32_e32 v148, v148, v197
	v_sub_f32_e32 v149, v149, v197
	v_sub_f32_e32 v150, v150, v197
	v_sub_f32_e32 v151, v151, v197
	v_sub_f32_e32 v152, v152, v197
	v_sub_f32_e32 v153, v153, v197
	v_sub_f32_e32 v154, v154, v197
	v_sub_f32_e32 v155, v155, v197
	v_sub_f32_e32 v156, v156, v197
	v_sub_f32_e32 v157, v157, v197
	v_sub_f32_e32 v158, v158, v197
	v_sub_f32_e32 v159, v159, v197
	v_sub_f32_e32 v198, v198, v197
	v_sub_f32_e32 v199, v199, v197
	v_sub_f32_e32 v200, v200, v197
	v_sub_f32_e32 v201, v201, v197
	v_sub_f32_e32 v202, v202, v197
	v_sub_f32_e32 v203, v203, v197
	v_sub_f32_e32 v204, v204, v197
	v_sub_f32_e32 v205, v205, v197
	v_sub_f32_e32 v206, v206, v197
	v_sub_f32_e32 v207, v207, v197
	v_sub_f32_e32 v208, v208, v197
	v_sub_f32_e32 v209, v209, v197
	v_sub_f32_e32 v210, v210, v197
	v_sub_f32_e32 v211, v211, v197
	v_sub_f32_e32 v212, v212, v197
	v_sub_f32_e32 v213, v213, v197
	v_cmp_gt_f32_e64 s[12:13], 1.0, v242
.Lmla_ok_B:
	s_waitcnt lgkmcnt(6)
	v_mfma_f32_32x32x16_bf16 v[32:47], v[68:71], v[88:91], v[32:47]
	ds_read_b64_tr_b16 v[222:223], v183 offset:9216
	ds_read_b64_tr_b16 v[224:225], v183 offset:11264
	v_exp_f32_e32 v128, v128
	v_exp_f32_e32 v129, v129
	v_exp_f32_e32 v130, v130
	s_waitcnt lgkmcnt(6)
	v_mfma_f32_32x32x16_bf16 v[16:31], v[68:71], v[92:95], v[16:31]
	ds_read_b64_tr_b16 v[226:227], v183 offset:9728
	ds_read_b64_tr_b16 v[228:229], v183 offset:11776
	v_exp_f32_e32 v131, v131
	v_exp_f32_e32 v132, v132
	v_exp_f32_e32 v133, v133
	s_waitcnt lgkmcnt(6)
	v_mfma_f32_32x32x16_bf16 v[0:15], v[80:83], v[214:217], v[0:15]
	ds_read_b64_tr_b16 v[72:73], v183 offset:12288
	ds_read_b64_tr_b16 v[74:75], v183 offset:14336
	v_exp_f32_e32 v134, v134
	v_exp_f32_e32 v135, v135
	v_exp_f32_e32 v136, v136
	s_waitcnt lgkmcnt(6)
	v_mfma_f32_32x32x16_bf16 v[48:63], v[80:83], v[218:221], v[48:63]
	ds_read_b64_tr_b16 v[76:77], v183 offset:12800
	ds_read_b64_tr_b16 v[78:79], v183 offset:14848
	v_exp_f32_e32 v137, v137
	v_exp_f32_e32 v138, v138
	v_exp_f32_e32 v139, v139
	s_waitcnt lgkmcnt(6)
	v_mfma_f32_32x32x16_bf16 v[32:47], v[80:83], v[222:225], v[32:47]
	ds_read_b64_tr_b16 v[88:89], v183 offset:13312
	ds_read_b64_tr_b16 v[90:91], v183 offset:15360
	v_exp_f32_e32 v140, v140
	v_exp_f32_e32 v141, v141
	v_exp_f32_e32 v142, v142
	s_waitcnt lgkmcnt(6)
	v_mfma_f32_32x32x16_bf16 v[16:31], v[80:83], v[226:229], v[16:31]
	ds_read_b64_tr_b16 v[92:93], v183 offset:13824
	ds_read_b64_tr_b16 v[94:95], v183 offset:15872
	v_exp_f32_e32 v143, v143
	s_waitcnt lgkmcnt(6)
	v_mfma_f32_32x32x16_bf16 v[0:15], v[84:87], v[72:75], v[0:15]
	s_waitcnt lgkmcnt(4)
	v_mfma_f32_32x32x16_bf16 v[48:63], v[84:87], v[76:79], v[48:63]
	s_waitcnt lgkmcnt(2)
	v_mfma_f32_32x32x16_bf16 v[32:47], v[84:87], v[88:91], v[32:47]
	s_waitcnt lgkmcnt(0)
	v_mfma_f32_32x32x16_bf16 v[16:31], v[84:87], v[92:95], v[16:31]
	s_cmp_lg_u64 s[12:13], 0
	s_cbranch_scc0 .Lmla_nors_B
	s_and_saveexec_b64 s[20:21], s[40:41]
	ds_write_b32 v162, v242 offset:128
	s_or_b64 exec, exec, s[20:21]
	s_waitcnt lgkmcnt(0)
	v_add_u32_e32 v245, s37, v184
	ds_read_b128 v[214:217], v245 offset:128
	ds_read_b128 v[218:221], v245 offset:160
	ds_read_b128 v[222:225], v245 offset:192
	ds_read_b128 v[226:229], v245 offset:224
	s_waitcnt lgkmcnt(0)
	v_pk_mul_f32 v[0:1], v[0:1], v[214:215]
	v_pk_mul_f32 v[2:3], v[2:3], v[216:217]
	v_pk_mul_f32 v[4:5], v[4:5], v[218:219]
	v_pk_mul_f32 v[6:7], v[6:7], v[220:221]
	v_pk_mul_f32 v[8:9], v[8:9], v[222:223]
	v_pk_mul_f32 v[10:11], v[10:11], v[224:225]
	v_pk_mul_f32 v[12:13], v[12:13], v[226:227]
	v_pk_mul_f32 v[14:15], v[14:15], v[228:229]
	v_pk_mul_f32 v[48:49], v[48:49], v[214:215]
	v_pk_mul_f32 v[50:51], v[50:51], v[216:217]
	v_pk_mul_f32 v[52:53], v[52:53], v[218:219]
	v_pk_mul_f32 v[54:55], v[54:55], v[220:221]
	v_pk_mul_f32 v[56:57], v[56:57], v[222:223]
	v_pk_mul_f32 v[58:59], v[58:59], v[224:225]
	v_pk_mul_f32 v[60:61], v[60:61], v[226:227]
	v_pk_mul_f32 v[62:63], v[62:63], v[228:229]
	v_pk_mul_f32 v[32:33], v[32:33], v[214:215]
	v_pk_mul_f32 v[34:35], v[34:35], v[216:217]
	v_pk_mul_f32 v[36:37], v[36:37], v[218:219]
	v_pk_mul_f32 v[38:39], v[38:39], v[220:221]
	v_pk_mul_f32 v[40:41], v[40:41], v[222:223]
	v_pk_mul_f32 v[42:43], v[42:43], v[224:225]
	v_pk_mul_f32 v[44:45], v[44:45], v[226:227]
	v_pk_mul_f32 v[46:47], v[46:47], v[228:229]
	v_pk_mul_f32 v[16:17], v[16:17], v[214:215]
	v_pk_mul_f32 v[18:19], v[18:19], v[216:217]
	v_pk_mul_f32 v[20:21], v[20:21], v[218:219]
	v_pk_mul_f32 v[22:23], v[22:23], v[220:221]
	v_pk_mul_f32 v[24:25], v[24:25], v[222:223]
	v_pk_mul_f32 v[26:27], v[26:27], v[224:225]
	v_pk_mul_f32 v[28:29], v[28:29], v[226:227]
	v_pk_mul_f32 v[30:31], v[30:31], v[228:229]
